# v77 + th0: thin stage 0/1 K=1024 operand loads issued with the K=256 loads (dead regs v68-135), own bf16 partial forwarded in register
# speedup vs baseline: 1.0037x; 1.0037x over previous
.LBB0_864:
	s_or_b64 exec, exec, s[6:7]
	v_readlane_b32 s0, v246, 0
	v_readlane_b32 s1, v246, 1
	s_barrier
	s_load_dwordx2 s[0:1], s[0:1], 0xa8
	s_and_b32 s2, s31, 0xffffffe0
	s_add_i32 s2, s2, 0x8000
	v_lshrrev_b32_e32 v24, 4, v0
	v_or_b32_e32 v2, s2, v24
	s_lshl_b32 s3, s86, 4
	v_ashrrev_i32_e32 v3, 31, v2
	s_and_b32 s3, s3, 0x3f0
	v_lshlrev_b64 v[2:3], 11, v[2:3]
	v_or_b32_e32 v14, s3, v1
	v_mov_b32_e32 v15, 0
	s_waitcnt lgkmcnt(0)
	v_lshl_add_u64 v[16:17], s[0:1], 0, v[2:3]
	v_lshl_add_u64 v[2:3], v[16:17], 0, v[14:15]
	s_mov_b32 s4, 0xb600000
	v_add_co_u32_e32 v50, vcc, s4, v2
	s_mul_hi_i32 s4, s2, 0xa00
	s_mulk_i32 s2, 0xa00
	s_add_u32 s8, s0, s2
	v_addc_co_u32_e32 v51, vcc, 0, v3, vcc
	v_mul_u32_u24_e32 v2, 0xa00, v1
	v_mov_b32_e32 v3, v15
	s_addc_u32 s9, s1, s4
	s_mov_b32 s7, 0
	v_lshl_add_u64 v[4:5], s[8:9], 0, v[2:3]
	s_lshl_b32 s6, s79, 6
	s_mulk_i32 s3, 0xa00
	v_lshl_add_u64 v[4:5], v[4:5], 0, s[6:7]
	v_and_b32_e32 v18, 48, v178
	v_mov_b32_e32 v19, v15
	v_lshl_add_u64 v[6:7], v[4:5], 0, v[18:19]
	s_add_u32 s10, s0, s3
	s_mov_b32 s2, 0x2400000
	s_addc_u32 s11, s1, 0
	v_add_co_u32_e32 v10, vcc, s2, v6
	v_lshl_add_u64 v[2:3], s[10:11], 0, v[2:3]
	s_nop 0
	v_addc_co_u32_e32 v11, vcc, 0, v7, vcc
	s_mov_b32 s3, 0x240a000
	v_lshl_add_u64 v[8:9], v[2:3], 0, s[6:7]
	v_add_co_u32_e32 v20, vcc, s3, v6
	s_mov_b32 s4, 0xe00000
	s_nop 0
	v_addc_co_u32_e32 v21, vcc, 0, v7, vcc
	v_lshl_add_u64 v[6:7], v[8:9], 0, v[18:19]
	v_add_co_u32_e32 v22, vcc, s4, v6
	global_load_ubyte v25, v[50:51], off
	global_load_dwordx4 v[2:5], v[10:11], off
	v_addc_co_u32_e32 v23, vcc, 0, v7, vcc
	global_load_dwordx4 v[6:9], v[20:21], off
	global_load_dwordx4 v[10:13], v[22:23], off
	v_mul_u32_u24_e32 v68, 0xa00, v1
	v_mov_b32_e32 v69, 0
	s_lshl_b32 s98, s79, 8
	s_mov_b32 s99, 0
	v_lshl_add_u64 v[70:71], s[10:11], 0, v[68:69]
	v_lshl_add_u64 v[72:73], s[8:9], 0, v[68:69]
	v_lshl_add_u64 v[70:71], v[70:71], 0, s[98:99]
	v_lshl_add_u64 v[72:73], v[72:73], 0, s[98:99]
	v_lshl_add_u64 v[70:71], v[70:71], 0, v[18:19]
	v_lshl_add_u64 v[72:73], v[72:73], 0, v[18:19]
	s_mov_b32 s98, 0xe00000
	s_mov_b32 s100, 0x2400000
	s_mov_b32 s101, 0
	v_lshl_add_u64 v[74:75], v[70:71], 0, s[98:99]
	v_lshl_add_u64 v[76:77], v[72:73], 0, s[100:101]
	s_mov_b32 s98, 0x2400200
	s_mov_b32 s100, 0x240a000
	v_lshl_add_u64 v[78:79], v[72:73], 0, s[98:99]
	v_lshl_add_u64 v[80:81], v[72:73], 0, s[100:101]
	s_mov_b32 s98, 0xe00200
	s_nop 0
	v_lshl_add_u64 v[82:83], v[70:71], 0, s[98:99]
	global_load_dwordx4 v[84:87], v[76:77], off offset:512
	global_load_dwordx4 v[88:91], v[80:81], off offset:512
	global_load_ubyte v92, v[50:51], off offset:1024
	global_load_dwordx4 v[96:99], v[78:79], off offset:64
	global_load_dwordx4 v[100:103], v[82:83], off offset:64
	global_load_dwordx4 v[104:107], v[82:83], off offset:128
	global_load_dwordx4 v[108:111], v[80:81], off offset:576
	global_load_dwordx4 v[112:115], v[80:81], off offset:640
	global_load_dwordx4 v[116:119], v[74:75], off offset:512
	global_load_dwordx4 v[120:123], v[82:83], off offset:192
	global_load_dwordx4 v[124:127], v[78:79], off offset:128
	global_load_dwordx4 v[128:131], v[78:79], off offset:192
	global_load_dwordx4 v[132:135], v[80:81], off offset:704
	s_waitcnt vmcnt(16)
	v_cvt_f32_ubyte0_e32 v20, v25
	s_waitcnt vmcnt(13)
	v_mfma_f32_16x16x32_bf16 v[2:5], v[2:5], v[10:13], 0
	v_lshlrev_b32_e32 v21, 4, v178
	v_lshl_add_u32 v64, v1, 2, 0
	v_and_b32_e32 v65, 0x300, v21
	v_mfma_f32_16x16x32_bf16 v[6:9], v[6:9], v[10:13], 0
	s_lshl_b32 s5, s79, 11
	v_add3_u32 v21, v64, v65, s5
	s_nop 1
	ds_write2_b32 v21, v2, v3 offset1:16
	ds_write2_b32 v21, v4, v5 offset0:32 offset1:48
	v_add_u32_e32 v2, 0x400, v21
	v_lshl_add_u32 v66, v24, 6, v64
	ds_write2_b32 v2, v6, v7 offset1:16
	ds_write2_b32 v2, v8, v9 offset0:32 offset1:48
	s_waitcnt lgkmcnt(0)
	s_barrier
	ds_read2st64_b32 v[2:3], v66 offset1:8
	ds_read2st64_b32 v[4:5], v66 offset0:16 offset1:24
	ds_read2st64_b32 v[6:7], v66 offset0:32 offset1:40
	s_movk_i32 s12, 0x7fff
	v_lshlrev_b32_e32 v14, 1, v14
	s_waitcnt lgkmcnt(2)
	v_add_f32_e32 v2, 0, v2
	v_add_f32_e32 v8, v2, v3
	ds_read2st64_b32 v[2:3], v66 offset0:48 offset1:56
	s_waitcnt lgkmcnt(2)
	v_add_f32_e32 v4, v8, v4
	v_add_f32_e32 v4, v4, v5
	s_waitcnt lgkmcnt(1)
	v_add_f32_e32 v4, v4, v6
	v_add_f32_e32 v4, v4, v7
	s_waitcnt lgkmcnt(0)
	v_add_f32_e32 v2, v4, v2
	v_add_f32_e32 v2, v2, v3
	v_mul_f32_e32 v3, 0x3b808081, v20
	v_mul_f32_e32 v2, v3, v2
	v_bfe_u32 v3, v2, 16, 1
	v_add3_u32 v4, v2, v3, s12
	v_mov_b32_e32 v93, v4
	v_lshl_add_u64 v[2:3], v[16:17], 0, v[14:15]
	s_mov_b32 s0, 0x7500000
	v_add_co_u32_e32 v52, vcc, s0, v2
	v_mul_u32_u24_e32 v1, 0x500, v1
	s_nop 0
	v_addc_co_u32_e32 v53, vcc, 0, v3, vcc
	v_lshlrev_b32_e32 v14, 1, v1
	global_store_short_d16_hi v[52:53], v4, off
	s_lshl_b32 s6, s79, 8
	v_lshl_add_u64 v[4:5], s[10:11], 0, v[14:15]
	v_lshl_add_u64 v[4:5], v[4:5], 0, s[6:7]
	v_lshl_add_u64 v[2:3], s[8:9], 0, v[14:15]
	v_lshl_add_u64 v[4:5], v[4:5], 0, v[18:19]
	v_lshl_add_u64 v[2:3], v[2:3], 0, s[6:7]
	v_add_co_u32_e32 v58, vcc, s4, v4
	v_lshl_add_u64 v[2:3], v[2:3], 0, v[18:19]
	s_nop 0
	v_addc_co_u32_e32 v59, vcc, 0, v5, vcc
	v_add_co_u32_e32 v60, vcc, s2, v2
	s_mov_b64 s[0:1], 0x2400200
	s_nop 0
	v_addc_co_u32_e32 v61, vcc, 0, v3, vcc
	v_lshl_add_u64 v[54:55], v[2:3], 0, s[0:1]
	s_mov_b64 s[0:1], 0xe00200
	v_add_co_u32_e32 v62, vcc, s3, v2
	s_barrier
	v_lshl_add_u64 v[56:57], v[4:5], 0, s[0:1]
	v_addc_co_u32_e32 v63, vcc, 0, v3, vcc
	s_waitcnt vmcnt(1)
	v_cvt_f32_ubyte0_e32 v1, v92
	s_nop 0
	v_and_b32_e32 v50, 0xffff0000, v93
	s_nop 0
	v_mfma_f32_16x16x32_bf16 v[2:5], v[84:87], v[116:119], 0
	v_mul_f32_e32 v1, 0x3b808081, v1
	v_cmp_lt_i32_e32 vcc, 63, v0
	s_mov_b64 s[8:9], 0
	v_mfma_f32_16x16x32_bf16 v[6:9], v[88:91], v[116:119], 0
	v_mfma_f32_16x16x32_bf16 v[2:5], v[96:99], v[100:103], v[2:5]
	v_add3_u32 v10, v64, s5, v65
	v_mfma_f32_16x16x32_bf16 v[6:9], v[108:111], v[100:103], v[6:9]
	s_nop 0
	v_mfma_f32_16x16x32_bf16 v[2:5], v[124:127], v[104:107], v[2:5]
	v_mfma_f32_16x16x32_bf16 v[6:9], v[112:115], v[104:107], v[6:9]
	s_nop 0
	v_mfma_f32_16x16x32_bf16 v[2:5], v[128:131], v[120:123], v[2:5]
	s_nop 7
	ds_write2_b32 v10, v2, v3 offset1:16
	ds_write2_b32 v10, v4, v5 offset0:32 offset1:48
	s_nop 0
	v_mfma_f32_16x16x32_bf16 v[2:5], v[132:135], v[120:123], v[6:9]
	v_add_u32_e32 v10, 0x400, v10
	s_nop 6
	ds_write2_b32 v10, v2, v3 offset1:16
	ds_write2_b32 v10, v4, v5 offset0:32 offset1:48
	s_waitcnt lgkmcnt(0)
	s_barrier
	ds_read2st64_b32 v[2:3], v66 offset1:8
	ds_read2st64_b32 v[4:5], v66 offset0:16 offset1:24
	ds_read2st64_b32 v[6:7], v66 offset0:32 offset1:40
	s_waitcnt lgkmcnt(2)
	v_add_f32_e32 v2, 0, v2
	v_add_f32_e32 v8, v2, v3
	ds_read2st64_b32 v[2:3], v66 offset0:48 offset1:56
	s_waitcnt lgkmcnt(2)
	v_add_f32_e32 v4, v8, v4
	v_add_f32_e32 v4, v4, v5
	s_waitcnt lgkmcnt(1)
	v_add_f32_e32 v4, v4, v6
	v_add_f32_e32 v4, v4, v7
	s_waitcnt lgkmcnt(0)
	v_add_f32_e32 v2, v4, v2
	v_add_f32_e32 v2, v2, v3
	v_fmac_f32_e32 v50, v1, v2
	v_bfe_u32 v1, v50, 16, 1
	v_add3_u32 v1, v50, v1, s12
	global_store_short_d16_hi v[52:53], v1, off
	s_barrier
	s_waitcnt vmcnt(0)
	s_barrier
	s_and_saveexec_b64 s[0:1], vcc
	s_xor_b64 s[6:7], exec, s[0:1]
	s_cbranch_execnz .LBB0_880
	s_or_saveexec_b64 s[6:7], s[6:7]
	v_mov_b64_e32 v[2:3], s[10:11]
	s_xor_b64 exec, exec, s[6:7]
	s_cbranch_execnz .LBB0_887
